# GDN scan compute wave: counted lgkmcnt waits (only the fragment an MFMA needs) in W.S / q.S+A.v sections, on top of silu(z) hoist
# baseline (speedup 1.0000x reference)
.Lcw_compute:
	s_add_i32 s0, s57, -1
	s_and_b32 s0, s0, 1
	s_mul_i32 s1, s0, 0xe000
	s_add_i32 s1, s1, 0
	v_add_u32_e32 v2, s1, v172
	v_add_u32_e32 v4, v2, v173
	ds_read_b128 v[102:105], v4
	v_cvt_pk_bf16_f32 v110, v22, v23
	v_cvt_pk_bf16_f32 v111, v24, v25
	v_cvt_pk_bf16_f32 v112, v6, v7
	v_cvt_pk_bf16_f32 v113, v8, v9
	v_cvt_pk_bf16_f32 v114, v10, v11
	v_cvt_pk_bf16_f32 v115, v12, v13
	v_cvt_pk_bf16_f32 v116, v18, v19
	v_cvt_pk_bf16_f32 v117, v20, v21
	v_add_u32_e32 v5, v2, v176
	ds_read_b128 v[106:109], v5
	ds_read_b128 v[130:133], v4 offset:4096
	s_waitcnt lgkmcnt(2)
	v_mfma_f32_16x16x32_bf16 v[134:137], v[102:105], v[110:113], v[94:97]
	v_mov_b32_e32 v221, 0
	s_add_i32 s58, s29, 1
	s_cmpk_lg_i32 s56, 0xfc0
	s_cselect_b32 s31, s58, 63
	v_cvt_pk_bf16_f32 v118, v30, v31
	v_cvt_pk_bf16_f32 v119, v32, v33
	v_cvt_pk_bf16_f32 v120, v26, v27
	v_mfma_f32_16x16x32_bf16 v[98:101], v[102:105], v[114:117], v[98:101]
	s_add_u32 s38, s34, s31
	v_mov_b32_e32 v228, v180
	s_addc_u32 s39, s35, 0
	s_bitcmp1_b32 s57, 0
	v_cvt_pk_bf16_f32 v121, v28, v29
	v_cvt_pk_bf16_f32 v122, v14, v15
	v_cvt_pk_bf16_f32 v123, v16, v17
	v_cvt_pk_bf16_f32 v124, v34, v35
	v_cvt_pk_bf16_f32 v125, v36, v37
	v_add_u32_e32 v244, v2, v178
	ds_read_b128 v[102:105], v244
	ds_read_b128 v[204:207], v5 offset:4096
	s_waitcnt lgkmcnt(3)
	v_mfma_f32_16x16x32_bf16 v[134:137], v[106:109], v[118:121], v[134:137]
	v_ashrrev_i32_e32 v229, 4, v228
	v_add_u32_e32 v220, s52, v229
	s_cselect_b32 s72, 0xe000, 0
	v_xor_b32_e32 v222, v220, v228
	v_cvt_pk_bf16_f32 v126, v38, v39
	v_cvt_pk_bf16_f32 v127, v40, v41
	v_cvt_pk_bf16_f32 v128, v62, v63
	v_mfma_f32_16x16x32_bf16 v[106:109], v[106:109], v[122:125], v[98:101]
	s_add_i32 s37, s27, s72
	v_ashrrev_i32_e32 v230, 3, v228
	s_lshl_b64 s[72:73], s[38:39], 13
	s_lshl_b64 s[60:61], s[38:39], 14
	v_cvt_pk_bf16_f32 v129, v64, v65
	v_cvt_pk_bf16_f32 v94, v42, v43
	v_cvt_pk_bf16_f32 v95, v44, v45
	s_waitcnt lgkmcnt(2)
	v_mfma_f32_16x16x32_bf16 v[86:89], v[130:133], v[110:113], v[86:89]
	v_lshlrev_b32_e32 v220, 7, v220
	v_lshlrev_b32_e32 v222, 3, v222
	s_add_u32 s62, s43, s60
	v_and_or_b32 v220, v222, s50, v220
	v_cvt_pk_bf16_f32 v96, v50, v51
	v_cvt_pk_bf16_f32 v97, v52, v53
	v_add_u32_e32 v245, v2, v179
	v_mfma_f32_16x16x32_bf16 v[90:93], v[130:133], v[114:117], v[90:93]
	v_add_u32_e32 v222, s53, v230
	s_addc_u32 s63, s44, s61
	v_lshrrev_b32_e32 v223, 1, v222
	s_add_u32 s64, s15, s60
	ds_read_b128 v[208:211], v245
	ds_read_b128 v[212:215], v244 offset:4096
	v_cvt_pk_bf16_f32 v98, v58, v59
	v_cvt_pk_bf16_f32 v99, v60, v61
	s_waitcnt lgkmcnt(3)
	v_mfma_f32_16x16x32_bf16 v[134:137], v[102:105], v[126:129], v[134:137]
	v_xor_b32_e32 v223, v223, v228
	s_addc_u32 s65, s19, s61
	s_add_i32 s59, s37, 0x4000
	v_lshlrev_b32_e32 v222, 6, v222
	v_cvt_pk_bf16_f32 v100, v46, v47
	v_cvt_pk_bf16_f32 v101, v48, v49
	v_cvt_pk_bf16_f32 v216, v54, v55
	v_mfma_f32_16x16x32_bf16 v[102:105], v[102:105], v[94:97], v[106:109]
	v_lshlrev_b32_e32 v223, 3, v223
	v_lshlrev_b64 v[224:225], 1, v[220:221]
	s_add_u32 s60, s45, s60
	v_and_or_b32 v222, v223, 56, v222
	v_cvt_pk_bf16_f32 v217, v56, v57
	v_cvt_pk_bf16_f32 v218, v66, v67
	v_cvt_pk_bf16_f32 v219, v68, v69
	ds_read_b128 v[106:109], v245 offset:4096
	s_waitcnt lgkmcnt(3)
	v_mfma_f32_16x16x32_bf16 v[86:89], v[204:207], v[118:121], v[86:89]
	v_lshl_add_u64 v[226:227], s[62:63], 0, v[224:225]
	s_mov_b32 m0, s37
	v_mov_b32_e32 v223, v3
	s_addc_u32 s61, s46, s61
	v_mfma_f32_16x16x32_bf16 v[90:93], v[204:207], v[122:125], v[90:93]
	s_add_i32 s66, s37, 0x8000
	global_load_lds_dwordx4 v[226:227], off
	v_lshl_add_u64 v[224:225], s[64:65], 0, v[224:225]
	s_mov_b32 m0, s59
	s_waitcnt lgkmcnt(1)
	v_mfma_f32_16x16x32_bf16 v[86:89], v[212:215], v[126:129], v[86:89]
	v_lshlrev_b64 v[222:223], 1, v[222:223]
	global_load_lds_dwordx4 v[224:225], off
	v_lshl_add_u64 v[224:225], s[60:61], 0, v[222:223]
	s_mov_b32 m0, s66
	v_mfma_f32_16x16x32_bf16 v[90:93], v[212:215], v[94:97], v[90:93]
	v_add_u32_e32 v220, s54, v229
	global_load_lds_dwordx4 v[224:225], off
	v_xor_b32_e32 v224, v220, v228
	v_lshlrev_b32_e32 v220, 7, v220
	s_waitcnt lgkmcnt(0)
	v_mfma_f32_16x16x32_bf16 v[86:89], v[106:109], v[98:101], v[86:89]
	v_lshlrev_b32_e32 v224, 3, v224
	v_and_or_b32 v220, v224, s50, v220
	v_add_u32_e32 v224, s55, v230
	v_lshrrev_b32_e32 v225, 1, v224
	v_mfma_f32_16x16x32_bf16 v[90:93], v[106:109], v[216:219], v[90:93]
	v_lshlrev_b64 v[226:227], 1, v[220:221]
	v_xor_b32_e32 v225, v225, v228
	v_lshl_add_u64 v[228:229], s[62:63], 0, v[226:227]
	s_add_i32 m0, s37, 0x2000
	ds_read_b128 v[106:109], v4 offset:8192
	ds_read_b128 v[130:133], v4 offset:12288
	s_waitcnt lgkmcnt(1)
	v_mfma_f32_16x16x32_bf16 v[78:81], v[106:109], v[110:113], v[78:81]
	v_lshlrev_b32_e32 v224, 6, v224
	v_lshlrev_b32_e32 v225, 3, v225
	global_load_lds_dwordx4 v[228:229], off
	v_lshl_add_u64 v[226:227], s[64:65], 0, v[226:227]
	v_mfma_f32_16x16x32_bf16 v[82:85], v[106:109], v[114:117], v[82:85]
	s_add_i32 m0, s37, 0x6000
	v_and_or_b32 v224, v225, 56, v224
	global_load_lds_dwordx4 v[226:227], off
	v_mov_b32_e32 v225, v3
	ds_read_b128 v[106:109], v5 offset:8192
	ds_read_b128 v[204:207], v5 offset:12288
	s_waitcnt lgkmcnt(2)
	v_mfma_f32_16x16x32_bf16 v[70:73], v[130:133], v[110:113], v[70:73]
	s_add_i32 m0, s37, 0xa000
	v_lshl_add_u64 v[224:225], v[224:225], 1, s[60:61]
	s_add_u32 s72, s33, s72
	global_load_lds_dwordx4 v[224:225], off
	v_mfma_f32_16x16x32_bf16 v[134:137], v[208:211], v[98:101], v[134:137]
	s_addc_u32 s73, s40, s73
	s_add_i32 m0, s37, 0xc000
	v_lshl_add_u64 v[222:223], s[72:73], 0, v[222:223]
	s_and_b64 s[72:73], s[24:25], exec
	v_mfma_f32_16x16x32_bf16 v[102:105], v[208:211], v[216:219], v[102:105]
	s_cselect_b32 s72, s31, s29
	s_mul_hi_u32 s73, s26, s72
	s_mul_i32 s72, s26, s72
	global_load_lds_dwordx4 v[222:223], off
	s_waitcnt lgkmcnt(1)
	v_mfma_f32_16x16x32_bf16 v[78:81], v[106:109], v[118:121], v[78:81]
	v_lshl_add_u64 v[222:223], s[72:73], 1, v[162:163]
	s_mov_b32 s29, s9
	v_lshl_add_u64 v[224:225], v[222:223], 0, s[8:9]
	v_lshl_add_u64 v[226:227], v[222:223], 0, s[28:29]
	v_mfma_f32_16x16x32_bf16 v[82:85], v[106:109], v[122:125], v[82:85]
	s_mov_b32 s37, s9
	s_mov_b32 s31, s9
	v_lshl_add_u64 v[228:229], v[226:227], 0, s[8:9]
	global_load_dwordx2 v[170:171], v[222:223], off
	ds_read_b128 v[106:109], v244 offset:8192
	ds_read_b128 v[208:211], v244 offset:12288
	v_mfma_f32_16x16x32_bf16 v[74:77], v[130:133], v[114:117], v[74:77]
	global_load_dwordx2 v[168:169], v[224:225], off
	global_load_dwordx2 v[164:165], v[226:227], off
	global_load_dwordx2 v[160:161], v[228:229], off
	v_lshl_add_u64 v[224:225], v[222:223], 0, s[36:37]
	s_waitcnt lgkmcnt(2)
	v_mfma_f32_16x16x32_bf16 v[70:73], v[204:207], v[118:121], v[70:73]
	v_lshl_add_u64 v[222:223], v[222:223], 0, s[30:31]
	v_lshl_add_u64 v[226:227], v[224:225], 0, s[8:9]
	v_lshl_add_u64 v[228:229], v[222:223], 0, s[8:9]
	global_load_dwordx2 v[158:159], v[224:225], off
	s_waitcnt lgkmcnt(1)
	v_mfma_f32_16x16x32_bf16 v[78:81], v[106:109], v[126:129], v[78:81]
	global_load_dwordx2 v[156:157], v[226:227], off
	global_load_dwordx2 v[154:155], v[222:223], off
	global_load_dwordx2 v[152:153], v[228:229], off
	s_lshl_b64 s[72:73], s[38:39], 2
	v_mfma_f32_16x16x32_bf16 v[82:85], v[106:109], v[94:97], v[82:85]
	s_add_u32 s72, s41, s72
	s_addc_u32 s73, s42, s73
	global_load_dword v147, v3, s[72:73]
	ds_read_b128 v[106:109], v245 offset:8192
	ds_read_b128 v[212:215], v245 offset:12288
	v_mfma_f32_16x16x32_bf16 v[74:77], v[204:207], v[122:125], v[74:77]
	s_waitcnt lgkmcnt(2)
	v_mfma_f32_16x16x32_bf16 v[70:73], v[208:211], v[126:129], v[70:73]
	s_waitcnt lgkmcnt(1)
	v_mfma_f32_16x16x32_bf16 v[78:81], v[106:109], v[98:101], v[78:81]
	v_mfma_f32_16x16x32_bf16 v[82:85], v[106:109], v[216:219], v[82:85]
	v_mfma_f32_16x16x32_bf16 v[74:77], v[208:211], v[94:97], v[74:77]
	s_waitcnt lgkmcnt(0)
	v_mfma_f32_16x16x32_bf16 v[130:133], v[212:215], v[98:101], v[70:73]
	v_mfma_f32_16x16x32_bf16 v[206:209], v[212:215], v[216:219], v[74:77]
	s_nop 1
	ds_read_b128 v[70:73], v4 offset:16384
	ds_read_b128 v[210:213], v4 offset:20480
	ds_read_b128 v[220:223], v5 offset:16384
	ds_read_b128 v[224:227], v5 offset:20480
	ds_read_b128 v[228:231], v244 offset:16384
	s_waitcnt lgkmcnt(4)
	v_mfma_f32_16x16x32_bf16 v[74:77], v[70:73], v[110:113], 0
	v_mfma_f32_16x16x32_bf16 v[106:109], v[70:73], v[114:117], 0
	v_cvt_pk_bf16_f32 v70, v134, v135
	v_cvt_pk_bf16_f32 v71, v136, v137
	v_cvt_pk_bf16_f32 v72, v86, v87
	s_waitcnt lgkmcnt(2)
	v_mfma_f32_16x16x32_bf16 v[74:77], v[220:223], v[118:121], v[74:77]
	v_cvt_pk_bf16_f32 v73, v88, v89
	v_mfma_f32_16x16x32_bf16 v[134:137], v[220:223], v[122:125], v[106:109]
	ds_read_b128 v[220:223], v245 offset:16384
	ds_read_b128 v[232:235], v244 offset:20480
	s_nop 0
	v_add_u32_e32 v109, s1, v167
	s_waitcnt lgkmcnt(2)
	v_mfma_f32_16x16x32_bf16 v[74:77], v[228:231], v[126:129], v[74:77]
	v_add_u32_e32 v2, v109, v174
	v_cvt_pk_bf16_f32 v106, v78, v79
	v_add_u32_e32 v204, v109, v175
	v_mfma_f32_16x16x32_bf16 v[86:89], v[228:231], v[94:97], v[134:137]
	s_nop 2
	ds_read_b128 v[134:137], v2 offset:49152
	ds_read_b128 v[228:231], v245 offset:20480
	v_cvt_pk_bf16_f32 v107, v80, v81
	v_cvt_pk_bf16_f32 v108, v130, v131
	s_waitcnt lgkmcnt(3)
	v_mfma_f32_16x16x32_bf16 v[76:79], v[220:223], v[98:101], v[74:77]
	v_cvt_pk_bf16_f32 v109, v132, v133
	v_mfma_f32_16x16x32_bf16 v[86:89], v[220:223], v[216:219], v[86:89]
	ds_read_b128 v[220:223], v204 offset:49152
	ds_read_b128 v[236:239], v2 offset:51200
	v_cvt_pk_bf16_f32 v74, v102, v103
	v_cvt_pk_bf16_f32 v102, v82, v83
	s_waitcnt lgkmcnt(3)
	v_mfma_f32_16x16x32_bf16 v[78:81], v[134:137], v[70:73], v[76:79]
	v_cvt_pk_bf16_f32 v103, v84, v85
	v_cvt_pk_bf16_f32 v75, v104, v105
	v_cvt_pk_bf16_f32 v104, v206, v207
	s_waitcnt lgkmcnt(1)
	v_mfma_f32_16x16x32_bf16 v[240:243], v[220:223], v[106:109], v[78:81]
	v_cvt_pk_bf16_f32 v76, v90, v91
	v_cvt_pk_bf16_f32 v77, v92, v93
	ds_read_b128 v[90:93], v204 offset:51200
	v_mfma_f32_16x16x32_bf16 v[78:81], v[210:213], v[110:113], 0
	v_cvt_pk_bf16_f32 v105, v208, v209
	v_mfma_f32_16x16x32_bf16 v[82:85], v[210:213], v[114:117], 0
	v_mfma_f32_16x16x32_bf16 v[78:81], v[224:227], v[118:121], v[78:81]
	v_mfma_f32_16x16x32_bf16 v[82:85], v[224:227], v[122:125], v[82:85]
	v_mfma_f32_16x16x32_bf16 v[78:81], v[232:235], v[126:129], v[78:81]
	v_mfma_f32_16x16x32_bf16 v[82:85], v[232:235], v[94:97], v[82:85]
	v_mfma_f32_16x16x32_bf16 v[78:81], v[228:231], v[98:101], v[78:81]
	v_mfma_f32_16x16x32_bf16 v[82:85], v[228:231], v[216:219], v[82:85]
	s_waitcnt lgkmcnt(1)
	v_mfma_f32_16x16x32_bf16 v[78:81], v[236:239], v[70:73], v[78:81]
	v_mfma_f32_16x16x32_bf16 v[82:85], v[236:239], v[74:77], v[82:85]
	v_mfma_f32_16x16x32_bf16 v[86:89], v[134:137], v[74:77], v[86:89]
	s_waitcnt lgkmcnt(0)
	v_mfma_f32_16x16x32_bf16 v[134:137], v[90:93], v[106:109], v[78:81]
	v_mfma_f32_16x16x32_bf16 v[130:133], v[90:93], v[102:105], v[82:85]
	s_nop 2
	ds_read_b128 v[78:81], v4 offset:24576
	ds_read_b128 v[82:85], v4 offset:28672
	ds_read_b128 v[90:93], v5 offset:24576
	ds_read_b128 v[210:213], v5 offset:28672
	v_mfma_f32_16x16x32_bf16 v[206:209], v[220:223], v[102:105], v[86:89]
	s_waitcnt lgkmcnt(3)
	v_mfma_f32_16x16x32_bf16 v[86:89], v[78:81], v[110:113], 0
	v_mfma_f32_16x16x32_bf16 v[78:81], v[78:81], v[114:117], 0
	s_waitcnt lgkmcnt(1)
	v_mfma_f32_16x16x32_bf16 v[86:89], v[90:93], v[118:121], v[86:89]
	v_mfma_f32_16x16x32_bf16 v[78:81], v[90:93], v[122:125], v[78:81]
	ds_read_b128 v[90:93], v244 offset:24576
	ds_read_b128 v[220:223], v244 offset:28672
	s_waitcnt lgkmcnt(1)
	v_mfma_f32_16x16x32_bf16 v[86:89], v[90:93], v[126:129], v[86:89]
	v_mfma_f32_16x16x32_bf16 v[78:81], v[90:93], v[94:97], v[78:81]
	ds_read_b128 v[90:93], v245 offset:24576
	ds_read_b128 v[224:227], v245 offset:28672
	s_waitcnt lgkmcnt(1)
	v_mfma_f32_16x16x32_bf16 v[86:89], v[90:93], v[98:101], v[86:89]
	v_mfma_f32_16x16x32_bf16 v[78:81], v[90:93], v[216:219], v[78:81]
	ds_read_b128 v[90:93], v2 offset:53248
	ds_read_b128 v[228:231], v2 offset:55296
	ds_read_b128 v[232:235], v204 offset:53248
	ds_read_b128 v[236:239], v204 offset:55296
	s_waitcnt lgkmcnt(3)
	v_mfma_f32_16x16x32_bf16 v[86:89], v[90:93], v[70:73], v[86:89]
	v_mfma_f32_16x16x32_bf16 v[78:81], v[90:93], v[74:77], v[78:81]
	s_waitcnt lgkmcnt(1)
	v_mfma_f32_16x16x32_bf16 v[90:93], v[232:235], v[106:109], v[86:89]
	v_mfma_f32_16x16x32_bf16 v[86:89], v[232:235], v[102:105], v[78:81]
	v_mfma_f32_16x16x32_bf16 v[78:81], v[82:85], v[110:113], 0
	v_mfma_f32_16x16x32_bf16 v[82:85], v[82:85], v[114:117], 0
	v_mfma_f32_16x16x32_bf16 v[78:81], v[210:213], v[118:121], v[78:81]
	v_mfma_f32_16x16x32_bf16 v[82:85], v[210:213], v[122:125], v[82:85]
	v_mfma_f32_16x16x32_bf16 v[78:81], v[220:223], v[126:129], v[78:81]
	v_mfma_f32_16x16x32_bf16 v[82:85], v[220:223], v[94:97], v[82:85]
	v_mfma_f32_16x16x32_bf16 v[78:81], v[224:227], v[98:101], v[78:81]
	v_mfma_f32_16x16x32_bf16 v[82:85], v[224:227], v[216:219], v[82:85]
	v_mfma_f32_16x16x32_bf16 v[78:81], v[228:231], v[70:73], v[78:81]
	v_mfma_f32_16x16x32_bf16 v[94:97], v[228:231], v[74:77], v[82:85]
	s_waitcnt lgkmcnt(0)
	v_mfma_f32_16x16x32_bf16 v[82:85], v[236:239], v[106:109], v[78:81]
	v_mfma_f32_16x16x32_bf16 v[78:81], v[236:239], v[102:105], v[94:97]
	v_mul_f32_e64 v4, v208, v208
	v_mul_f32_e64 v5, v209, v209
	s_nop 3
	v_pk_mul_f32 v[94:95], v[206:207], v[206:207]
	v_lshl_add_u32 v98, s0, 14, v193
	v_pk_fma_f32 v[96:97], v[242:243], v[242:243], v[4:5]
	v_pk_fma_f32 v[4:5], v[240:241], v[240:241], v[94:95]
	v_cvt_pk_bf16_f32 v95, v240, s0
	v_lshl_add_u32 v100, v149, 1, v98
	ds_write_b16 v100, v95
	v_cvt_pk_bf16_f32 v95, v206, s0
	v_lshl_add_u32 v101, v201, 1, v98
	v_cvt_pk_bf16_f32 v98, v241, s0
	ds_write_b16 v101, v95
	ds_write_b16 v100, v98 offset:256
	v_cvt_pk_bf16_f32 v98, v207, s0
	v_cvt_pk_bf16_f32 v99, v242, s0
	ds_write_b16 v101, v98 offset:256
	ds_write_b16 v100, v99 offset:512
	v_cvt_pk_bf16_f32 v99, v208, s0
	v_mov_b32_dpp v94, v4 quad_perm:[1,0,3,2] row_mask:0xf bank_mask:0xf bound_ctrl:1
	v_mov_b32_dpp v95, v5 quad_perm:[1,0,3,2] row_mask:0xf bank_mask:0xf bound_ctrl:1
	v_mov_b32_dpp v98, v96 quad_perm:[1,0,3,2] row_mask:0xf bank_mask:0xf bound_ctrl:1
	ds_write_b16 v101, v99 offset:512
	v_mov_b32_dpp v99, v97 quad_perm:[1,0,3,2] row_mask:0xf bank_mask:0xf bound_ctrl:1
	v_pk_add_f32 v[4:5], v[4:5], v[94:95]
	v_pk_add_f32 v[96:97], v[96:97], v[98:99]
	v_cvt_pk_bf16_f32 v110, v243, s0
	v_mov_b32_dpp v94, v4 quad_perm:[2,3,0,1] row_mask:0xf bank_mask:0xf bound_ctrl:1
	v_mov_b32_dpp v95, v5 quad_perm:[2,3,0,1] row_mask:0xf bank_mask:0xf bound_ctrl:1
	v_mov_b32_dpp v98, v96 quad_perm:[2,3,0,1] row_mask:0xf bank_mask:0xf bound_ctrl:1
	v_mov_b32_dpp v99, v97 quad_perm:[2,3,0,1] row_mask:0xf bank_mask:0xf bound_ctrl:1
	v_pk_add_f32 v[4:5], v[4:5], v[94:95]
	v_pk_add_f32 v[96:97], v[96:97], v[98:99]
	s_lshl_b32 s1, s0, 10
	v_mov_b32_dpp v94, v4 row_half_mirror row_mask:0xf bank_mask:0xf bound_ctrl:1
	v_mov_b32_dpp v95, v5 row_half_mirror row_mask:0xf bank_mask:0xf bound_ctrl:1
	v_mov_b32_dpp v98, v96 row_half_mirror row_mask:0xf bank_mask:0xf bound_ctrl:1
	v_mov_b32_dpp v99, v97 row_half_mirror row_mask:0xf bank_mask:0xf bound_ctrl:1
	v_pk_add_f32 v[4:5], v[4:5], v[94:95]
	v_pk_add_f32 v[96:97], v[96:97], v[98:99]
	ds_write_b16 v100, v110 offset:768
	v_cvt_pk_bf16_f32 v110, v209, s0
	v_mov_b32_dpp v94, v4 row_mirror row_mask:0xf bank_mask:0xf bound_ctrl:1
	v_mov_b32_dpp v95, v5 row_mirror row_mask:0xf bank_mask:0xf bound_ctrl:1
	v_mov_b32_dpp v98, v96 row_mirror row_mask:0xf bank_mask:0xf bound_ctrl:1
	v_mov_b32_dpp v99, v97 row_mirror row_mask:0xf bank_mask:0xf bound_ctrl:1
	ds_write_b16 v101, v110 offset:768
	v_add_u32_e32 v110, s1, v202
	s_and_saveexec_b64 s[38:39], s[4:5]
	v_pk_add_f32 v[96:97], v[96:97], v[98:99]
	v_pk_add_f32 v[94:95], v[4:5], v[94:95]
	ds_write_b128 v110, v[94:97]
	s_or_b64 exec, exec, s[38:39]
	v_pk_mul_f32 v[4:5], v[132:133], v[132:133]
	v_pk_mul_f32 v[94:95], v[130:131], v[130:131]
	v_pk_fma_f32 v[96:97], v[136:137], v[136:137], v[4:5]
	v_pk_fma_f32 v[4:5], v[134:135], v[134:135], v[94:95]
	v_cvt_pk_bf16_f32 v95, v134, s0
	ds_write_b16 v100, v95 offset:4096
	v_cvt_pk_bf16_f32 v95, v130, s0
	v_cvt_pk_bf16_f32 v98, v135, s0
	ds_write_b16 v101, v95 offset:4096
	ds_write_b16 v100, v98 offset:4352
	v_cvt_pk_bf16_f32 v98, v131, s0
	v_cvt_pk_bf16_f32 v99, v136, s0
	ds_write_b16 v101, v98 offset:4352
	ds_write_b16 v100, v99 offset:4608
	v_cvt_pk_bf16_f32 v99, v132, s0
	v_mov_b32_dpp v94, v4 quad_perm:[1,0,3,2] row_mask:0xf bank_mask:0xf bound_ctrl:1
	v_mov_b32_dpp v95, v5 quad_perm:[1,0,3,2] row_mask:0xf bank_mask:0xf bound_ctrl:1
	v_mov_b32_dpp v98, v96 quad_perm:[1,0,3,2] row_mask:0xf bank_mask:0xf bound_ctrl:1
	ds_write_b16 v101, v99 offset:4608
	v_mov_b32_dpp v99, v97 quad_perm:[1,0,3,2] row_mask:0xf bank_mask:0xf bound_ctrl:1
	v_pk_add_f32 v[4:5], v[4:5], v[94:95]
	v_pk_add_f32 v[96:97], v[96:97], v[98:99]
	v_cvt_pk_bf16_f32 v111, v137, s0
	v_mov_b32_dpp v94, v4 quad_perm:[2,3,0,1] row_mask:0xf bank_mask:0xf bound_ctrl:1
	v_mov_b32_dpp v95, v5 quad_perm:[2,3,0,1] row_mask:0xf bank_mask:0xf bound_ctrl:1
	v_mov_b32_dpp v98, v96 quad_perm:[2,3,0,1] row_mask:0xf bank_mask:0xf bound_ctrl:1
	v_mov_b32_dpp v99, v97 quad_perm:[2,3,0,1] row_mask:0xf bank_mask:0xf bound_ctrl:1
	v_pk_add_f32 v[4:5], v[4:5], v[94:95]
	v_pk_add_f32 v[96:97], v[96:97], v[98:99]
	ds_write_b16 v100, v111 offset:4864
	v_mov_b32_dpp v94, v4 row_half_mirror row_mask:0xf bank_mask:0xf bound_ctrl:1
	v_mov_b32_dpp v95, v5 row_half_mirror row_mask:0xf bank_mask:0xf bound_ctrl:1
	v_mov_b32_dpp v98, v96 row_half_mirror row_mask:0xf bank_mask:0xf bound_ctrl:1
	v_mov_b32_dpp v99, v97 row_half_mirror row_mask:0xf bank_mask:0xf bound_ctrl:1
	v_pk_add_f32 v[4:5], v[4:5], v[94:95]
	v_pk_add_f32 v[96:97], v[96:97], v[98:99]
	v_cvt_pk_bf16_f32 v111, v133, s0
	v_mov_b32_dpp v94, v4 row_mirror row_mask:0xf bank_mask:0xf bound_ctrl:1
	v_mov_b32_dpp v95, v5 row_mirror row_mask:0xf bank_mask:0xf bound_ctrl:1
	v_mov_b32_dpp v98, v96 row_mirror row_mask:0xf bank_mask:0xf bound_ctrl:1
	v_mov_b32_dpp v99, v97 row_mirror row_mask:0xf bank_mask:0xf bound_ctrl:1
	ds_write_b16 v101, v111 offset:4864
	s_and_saveexec_b64 s[38:39], s[4:5]
	v_pk_add_f32 v[96:97], v[96:97], v[98:99]
	v_pk_add_f32 v[94:95], v[4:5], v[94:95]
	ds_write_b128 v110, v[94:97] offset:64
	s_or_b64 exec, exec, s[38:39]
	v_pk_mul_f32 v[94:95], v[86:87], v[86:87]
	v_cvt_pk_bf16_f32 v86, v86, s0
	v_pk_mul_f32 v[4:5], v[88:89], v[88:89]
	ds_write_b16 v101, v86 offset:8192
	v_cvt_pk_bf16_f32 v86, v91, s0
	v_pk_fma_f32 v[96:97], v[92:93], v[92:93], v[4:5]
	v_pk_fma_f32 v[4:5], v[90:91], v[90:91], v[94:95]
	v_cvt_pk_bf16_f32 v90, v90, s0
	ds_write_b16 v100, v86 offset:8448
	v_cvt_pk_bf16_f32 v86, v87, s0
	v_cvt_pk_bf16_f32 v87, v92, s0
	ds_write_b16 v100, v90 offset:8192
	ds_write_b16 v101, v86 offset:8448
	ds_write_b16 v100, v87 offset:8704
	v_cvt_pk_bf16_f32 v87, v88, s0
	v_mov_b32_dpp v94, v4 quad_perm:[1,0,3,2] row_mask:0xf bank_mask:0xf bound_ctrl:1
	v_mov_b32_dpp v95, v5 quad_perm:[1,0,3,2] row_mask:0xf bank_mask:0xf bound_ctrl:1
	v_mov_b32_dpp v86, v96 quad_perm:[1,0,3,2] row_mask:0xf bank_mask:0xf bound_ctrl:1
	ds_write_b16 v101, v87 offset:8704
	v_mov_b32_dpp v87, v97 quad_perm:[1,0,3,2] row_mask:0xf bank_mask:0xf bound_ctrl:1
	v_pk_add_f32 v[4:5], v[4:5], v[94:95]
	v_pk_add_f32 v[86:87], v[96:97], v[86:87]
	v_cvt_pk_bf16_f32 v88, v93, s0
	v_mov_b32_dpp v94, v4 quad_perm:[2,3,0,1] row_mask:0xf bank_mask:0xf bound_ctrl:1
	v_mov_b32_dpp v95, v5 quad_perm:[2,3,0,1] row_mask:0xf bank_mask:0xf bound_ctrl:1
	v_mov_b32_dpp v90, v86 quad_perm:[2,3,0,1] row_mask:0xf bank_mask:0xf bound_ctrl:1
	v_mov_b32_dpp v91, v87 quad_perm:[2,3,0,1] row_mask:0xf bank_mask:0xf bound_ctrl:1
	v_pk_add_f32 v[4:5], v[4:5], v[94:95]
	v_pk_add_f32 v[86:87], v[86:87], v[90:91]
	ds_write_b16 v100, v88 offset:8960
	v_mov_b32_dpp v94, v4 row_half_mirror row_mask:0xf bank_mask:0xf bound_ctrl:1
	v_mov_b32_dpp v95, v5 row_half_mirror row_mask:0xf bank_mask:0xf bound_ctrl:1
	v_mov_b32_dpp v90, v86 row_half_mirror row_mask:0xf bank_mask:0xf bound_ctrl:1
	v_mov_b32_dpp v91, v87 row_half_mirror row_mask:0xf bank_mask:0xf bound_ctrl:1
	v_pk_add_f32 v[4:5], v[4:5], v[94:95]
	v_pk_add_f32 v[86:87], v[86:87], v[90:91]
	v_cvt_pk_bf16_f32 v88, v89, s0
	v_mov_b32_dpp v94, v4 row_mirror row_mask:0xf bank_mask:0xf bound_ctrl:1
	v_mov_b32_dpp v95, v5 row_mirror row_mask:0xf bank_mask:0xf bound_ctrl:1
	v_mov_b32_dpp v90, v86 row_mirror row_mask:0xf bank_mask:0xf bound_ctrl:1
	v_mov_b32_dpp v91, v87 row_mirror row_mask:0xf bank_mask:0xf bound_ctrl:1
	ds_write_b16 v101, v88 offset:8960
	s_and_saveexec_b64 s[38:39], s[4:5]
	v_pk_add_f32 v[88:89], v[86:87], v[90:91]
	v_pk_add_f32 v[86:87], v[4:5], v[94:95]
	ds_write_b128 v110, v[86:89] offset:128
	s_or_b64 exec, exec, s[38:39]
	v_pk_mul_f32 v[86:87], v[78:79], v[78:79]
	v_cvt_pk_bf16_f32 v78, v78, s0
	v_pk_mul_f32 v[4:5], v[80:81], v[80:81]
	ds_write_b16 v101, v78 offset:12288
	v_cvt_pk_bf16_f32 v78, v83, s0
	v_pk_fma_f32 v[88:89], v[84:85], v[84:85], v[4:5]
	v_pk_fma_f32 v[4:5], v[82:83], v[82:83], v[86:87]
	v_cvt_pk_bf16_f32 v82, v82, s0
	ds_write_b16 v100, v78 offset:12544
	v_cvt_pk_bf16_f32 v78, v79, s0
	v_cvt_pk_bf16_f32 v79, v84, s0
	ds_write_b16 v100, v82 offset:12288
	ds_write_b16 v101, v78 offset:12544
	ds_write_b16 v100, v79 offset:12800
	v_cvt_pk_bf16_f32 v79, v80, s0
	v_mov_b32_dpp v86, v4 quad_perm:[1,0,3,2] row_mask:0xf bank_mask:0xf bound_ctrl:1
	v_mov_b32_dpp v87, v5 quad_perm:[1,0,3,2] row_mask:0xf bank_mask:0xf bound_ctrl:1
	v_mov_b32_dpp v78, v88 quad_perm:[1,0,3,2] row_mask:0xf bank_mask:0xf bound_ctrl:1
	ds_write_b16 v101, v79 offset:12800
	v_mov_b32_dpp v79, v89 quad_perm:[1,0,3,2] row_mask:0xf bank_mask:0xf bound_ctrl:1
	v_pk_add_f32 v[4:5], v[4:5], v[86:87]
	v_pk_add_f32 v[78:79], v[88:89], v[78:79]
	v_cvt_pk_bf16_f32 v80, v85, s0
	v_mov_b32_dpp v86, v4 quad_perm:[2,3,0,1] row_mask:0xf bank_mask:0xf bound_ctrl:1
	v_mov_b32_dpp v87, v5 quad_perm:[2,3,0,1] row_mask:0xf bank_mask:0xf bound_ctrl:1
	v_mov_b32_dpp v82, v78 quad_perm:[2,3,0,1] row_mask:0xf bank_mask:0xf bound_ctrl:1
	v_mov_b32_dpp v83, v79 quad_perm:[2,3,0,1] row_mask:0xf bank_mask:0xf bound_ctrl:1
	v_pk_add_f32 v[4:5], v[4:5], v[86:87]
	v_pk_add_f32 v[78:79], v[78:79], v[82:83]
	ds_write_b16 v100, v80 offset:13056
	v_mov_b32_dpp v86, v4 row_half_mirror row_mask:0xf bank_mask:0xf bound_ctrl:1
	v_mov_b32_dpp v87, v5 row_half_mirror row_mask:0xf bank_mask:0xf bound_ctrl:1
	v_mov_b32_dpp v82, v78 row_half_mirror row_mask:0xf bank_mask:0xf bound_ctrl:1
	v_mov_b32_dpp v83, v79 row_half_mirror row_mask:0xf bank_mask:0xf bound_ctrl:1
	v_pk_add_f32 v[4:5], v[4:5], v[86:87]
	v_pk_add_f32 v[78:79], v[78:79], v[82:83]
	v_cvt_pk_bf16_f32 v80, v81, s0
	v_mov_b32_dpp v86, v4 row_mirror row_mask:0xf bank_mask:0xf bound_ctrl:1
	v_mov_b32_dpp v87, v5 row_mirror row_mask:0xf bank_mask:0xf bound_ctrl:1
	v_mov_b32_dpp v82, v78 row_mirror row_mask:0xf bank_mask:0xf bound_ctrl:1
	v_mov_b32_dpp v83, v79 row_mirror row_mask:0xf bank_mask:0xf bound_ctrl:1
	ds_write_b16 v101, v80 offset:13056
	s_and_saveexec_b64 s[38:39], s[4:5]
	v_pk_add_f32 v[80:81], v[78:79], v[82:83]
	v_pk_add_f32 v[78:79], v[4:5], v[86:87]
	ds_write_b128 v110, v[78:81] offset:192
	s_or_b64 exec, exec, s[38:39]
	ds_read_b128 v[78:81], v2 offset:32768
	ds_read_b128 v[82:85], v2 offset:34816
	v_pk_mul_f32 v[24:25], v[24:25], v[166:167] op_sel_hi:[1,0]
	v_pk_mul_f32 v[22:23], v[22:23], v[166:167] op_sel_hi:[1,0]
	v_pk_mul_f32 v[12:13], v[12:13], v[166:167] op_sel_hi:[1,0]
	v_pk_mul_f32 v[10:11], v[10:11], v[166:167] op_sel_hi:[1,0]
	v_pk_mul_f32 v[8:9], v[8:9], v[166:167] op_sel_hi:[1,0]
	v_pk_mul_f32 v[6:7], v[6:7], v[166:167] op_sel_hi:[1,0]
	v_pk_mul_f32 v[20:21], v[20:21], v[166:167] op_sel_hi:[1,0]
	s_waitcnt lgkmcnt(0)
	v_mfma_f32_16x16x32_bf16 v[22:25], v[78:81], v[70:73], v[22:25]
	v_mul_f32_e64 v18, v18, v166
	v_mul_f32_e64 v19, v19, v166
	v_pk_mul_f32 v[32:33], v[32:33], v[166:167] op_sel_hi:[1,0]
	v_pk_mul_f32 v[30:31], v[30:31], v[166:167] op_sel_hi:[1,0]
	v_mfma_f32_16x16x32_bf16 v[10:13], v[78:81], v[74:77], v[10:13]
	ds_read_b128 v[78:81], v204 offset:32768
	ds_read_b128 v[86:89], v204 offset:34816
	v_pk_mul_f32 v[16:17], v[16:17], v[166:167] op_sel_hi:[1,0]
	v_pk_mul_f32 v[14:15], v[14:15], v[166:167] op_sel_hi:[1,0]
	s_waitcnt lgkmcnt(0)
	v_mfma_f32_16x16x32_bf16 v[22:25], v[78:81], v[106:109], v[22:25]
	v_mul_f32_e64 v28, v28, v166
	v_mul_f32_e64 v29, v29, v166
	v_pk_mul_f32 v[26:27], v[26:27], v[166:167] op_sel_hi:[1,0]
	v_pk_mul_f32 v[36:37], v[36:37], v[166:167] op_sel_hi:[1,0]
	v_mfma_f32_16x16x32_bf16 v[10:13], v[78:81], v[102:105], v[10:13]
	ds_read_b128 v[78:81], v2 offset:36864
	v_pk_mul_f32 v[34:35], v[34:35], v[166:167] op_sel_hi:[1,0]
	v_pk_mul_f32 v[40:41], v[40:41], v[166:167] op_sel_hi:[1,0]
	v_mfma_f32_16x16x32_bf16 v[4:7], v[82:85], v[70:73], v[6:9]
	v_mul_f32_e64 v38, v38, v166
	v_mul_f32_e64 v39, v39, v166
	v_pk_mul_f32 v[44:45], v[44:45], v[166:167] op_sel_hi:[1,0]
	v_pk_mul_f32 v[42:43], v[42:43], v[166:167] op_sel_hi:[1,0]
	v_mfma_f32_16x16x32_bf16 v[18:21], v[82:85], v[74:77], v[18:21]
	ds_read_b128 v[82:85], v2 offset:38912
	v_pk_mul_f32 v[64:65], v[64:65], v[166:167] op_sel_hi:[1,0]
	v_pk_mul_f32 v[62:63], v[62:63], v[166:167] op_sel_hi:[1,0]
	v_mfma_f32_16x16x32_bf16 v[6:9], v[86:89], v[106:109], v[4:7]
	v_mul_f32_e64 v52, v52, v166
	v_mul_f32_e64 v53, v53, v166
	v_pk_mul_f32 v[50:51], v[50:51], v[166:167] op_sel_hi:[1,0]
	v_pk_mul_f32 v[60:61], v[60:61], v[166:167] op_sel_hi:[1,0]
	v_mfma_f32_16x16x32_bf16 v[18:21], v[86:89], v[102:105], v[18:21]
	v_mul_f32_e64 v58, v58, v166
	v_mul_f32_e64 v59, v59, v166
	v_pk_mul_f32 v[56:57], v[56:57], v[166:167] op_sel_hi:[1,0]
	v_pk_mul_f32 v[54:55], v[54:55], v[166:167] op_sel_hi:[1,0]
	s_waitcnt lgkmcnt(0)
	v_mfma_f32_16x16x32_bf16 v[30:33], v[78:81], v[70:73], v[30:33]
	v_mul_f32_e64 v48, v48, v166
	v_mul_f32_e64 v49, v49, v166
	v_pk_mul_f32 v[46:47], v[46:47], v[166:167] op_sel_hi:[1,0]
	v_pk_mul_f32 v[68:69], v[68:69], v[166:167] op_sel_hi:[1,0]
	v_mfma_f32_16x16x32_bf16 v[14:17], v[78:81], v[74:77], v[14:17]
	ds_read_b128 v[78:81], v204 offset:36864
	ds_read_b128 v[86:89], v204 offset:38912
	ds_read_b128 v[90:93], v204 offset:43008
	v_pk_mul_f32 v[66:67], v[66:67], v[166:167] op_sel_hi:[1,0]
	s_waitcnt lgkmcnt(0)
	v_mfma_f32_16x16x32_bf16 v[30:33], v[78:81], v[106:109], v[30:33]
	s_waitcnt vmcnt(0)
	v_lshlrev_b32_e32 v94, 16, v170
	v_and_b32_e32 v95, 0xffff0000, v170
	v_lshlrev_b32_e32 v96, 16, v171
	v_mfma_f32_16x16x32_bf16 v[14:17], v[78:81], v[102:105], v[14:17]
	ds_read_b128 v[78:81], v2 offset:40960
	v_and_b32_e32 v97, 0xffff0000, v171
	v_lshlrev_b32_e32 v98, 16, v168
	v_mfma_f32_16x16x32_bf16 v[26:29], v[82:85], v[70:73], v[26:29]
	v_and_b32_e32 v99, 0xffff0000, v168
	v_lshlrev_b32_e32 v100, 16, v169
	v_and_b32_e32 v101, 0xffff0000, v169
	v_mfma_f32_16x16x32_bf16 v[34:37], v[82:85], v[74:77], v[34:37]
	ds_read_b128 v[82:85], v204 offset:40960
	v_mov_b32_e32 v166, v147
	v_mfma_f32_16x16x32_bf16 v[26:29], v[86:89], v[106:109], v[26:29]
	v_mfma_f32_16x16x32_bf16 v[34:37], v[86:89], v[102:105], v[34:37]
	ds_read_b128 v[86:89], v2 offset:43008
	s_waitcnt lgkmcnt(2)
	v_mfma_f32_16x16x32_bf16 v[38:41], v[78:81], v[70:73], v[38:41]
	v_mfma_f32_16x16x32_bf16 v[42:45], v[78:81], v[74:77], v[42:45]
	ds_read_b128 v[78:81], v2 offset:45056
	ds_read_b128 v[110:113], v2 offset:47104
	s_waitcnt lgkmcnt(3)
	v_mfma_f32_16x16x32_bf16 v[38:41], v[82:85], v[106:109], v[38:41]
	v_mfma_f32_16x16x32_bf16 v[42:45], v[82:85], v[102:105], v[42:45]
	ds_read_b128 v[82:85], v204 offset:45056
	ds_read_b128 v[114:117], v204 offset:47104
	s_waitcnt lgkmcnt(4)
	v_mfma_f32_16x16x32_bf16 v[62:65], v[86:89], v[70:73], v[62:65]
	v_mfma_f32_16x16x32_bf16 v[50:53], v[86:89], v[74:77], v[50:53]
	v_lshlrev_b32_e32 v86, 16, v164
	v_and_b32_e32 v87, 0xffff0000, v164
	v_lshlrev_b32_e32 v88, 16, v165
	s_waitcnt lgkmcnt(3)
	v_mfma_f32_16x16x32_bf16 v[58:61], v[78:81], v[70:73], v[58:61]
	v_and_b32_e32 v89, 0xffff0000, v165
	v_mfma_f32_16x16x32_bf16 v[54:57], v[78:81], v[74:77], v[54:57]
	v_lshlrev_b32_e32 v78, 16, v158
	v_and_b32_e32 v79, 0xffff0000, v158
	v_lshlrev_b32_e32 v80, 16, v159
	s_waitcnt lgkmcnt(2)
	v_mfma_f32_16x16x32_bf16 v[46:49], v[110:113], v[70:73], v[46:49]
	v_and_b32_e32 v81, 0xffff0000, v159
	v_lshlrev_b32_e32 v70, 16, v154
	v_and_b32_e32 v71, 0xffff0000, v154
	v_mfma_f32_16x16x32_bf16 v[66:69], v[110:113], v[74:77], v[66:69]
	v_lshlrev_b32_e32 v72, 16, v155
	v_and_b32_e32 v73, 0xffff0000, v155
	v_lshlrev_b32_e32 v74, 16, v152
	v_mfma_f32_16x16x32_bf16 v[62:65], v[90:93], v[106:109], v[62:65]
	v_and_b32_e32 v75, 0xffff0000, v152
	v_lshlrev_b32_e32 v76, 16, v153
	v_and_b32_e32 v77, 0xffff0000, v153
	v_mfma_f32_16x16x32_bf16 v[50:53], v[90:93], v[102:105], v[50:53]
	v_lshlrev_b32_e32 v90, 16, v160
	v_and_b32_e32 v91, 0xffff0000, v160
	v_lshlrev_b32_e32 v92, 16, v161
	s_waitcnt lgkmcnt(1)
	v_mfma_f32_16x16x32_bf16 v[58:61], v[82:85], v[106:109], v[58:61]
	v_and_b32_e32 v93, 0xffff0000, v161
	v_mfma_f32_16x16x32_bf16 v[54:57], v[82:85], v[102:105], v[54:57]
	v_lshlrev_b32_e32 v82, 16, v156
	v_and_b32_e32 v83, 0xffff0000, v156
	v_lshlrev_b32_e32 v84, 16, v157
	s_waitcnt lgkmcnt(0)
	v_mfma_f32_16x16x32_bf16 v[46:49], v[114:117], v[106:109], v[46:49]
	v_and_b32_e32 v85, 0xffff0000, v157
	v_mfma_f32_16x16x32_bf16 v[66:69], v[114:117], v[102:105], v[66:69]
